# SwiGLU epilogue: batched independent silu chains, packed f32 multiplies and adds for the non-transcendental steps (same operation order)
# speedup vs baseline: 1.0167x; 1.0044x over previous
; __device__ __forceinline__ unsigned cvt_pk_bf16(float lo, float hi) { unsigned r; asm("v_cvt_pk_bf16_f32 %0, %1, %2" : "=v"(r) : "v"(lo), "v"(hi)); return r; }
; __device__ __forceinline__ float silu_f(float x) { return x * __builtin_amdgcn_rcpf(1.f + __expf(-x)); }
;     __device__ __forceinline__ void operator()(const f32x4 (&acc)[2][2][4][2], const Unit& u, int wr, int wc, int fr, int fq) const {
;         const int row0 = u.pm * BM + wr * 64 + fr, col = u.pn * 128 + wc * 32 + fq * 8;
; #pragma unroll
;         for (int ai = 0; ai < 2; ++ai)
; #pragma unroll
;             for (int m = 0; m < 4; ++m) {
;                 const f32x4 g0 = acc[ai][0][m][0], u0 = acc[ai][1][m][0], g1 = acc[ai][0][m][1], u1 = acc[ai][1][m][1];
;                 u32x4 w;
;                 w.x = cvt_pk_bf16(silu_f(g0[0]) * u0[0], silu_f(g0[1]) * u0[1]); w.y = cvt_pk_bf16(silu_f(g0[2]) * u0[2], silu_f(g0[3]) * u0[3]);
;                 w.z = cvt_pk_bf16(silu_f(g1[0]) * u1[0], silu_f(g1[1]) * u1[1]); w.w = cvt_pk_bf16(silu_f(g1[2]) * u1[2], silu_f(g1[3]) * u1[3]);
;                 *(u32x4*)(O + (size_t)u.pm * BM * DFF + (size_t)(col >> 6) * (BM * 64) + (size_t)(wr * 64 + fr + ai * HALF + m * 16) * 64 + (col & 63)) = w;
;             }
;     }
.LBB0_166:
	s_waitcnt vmcnt(0)
	s_lshl_b32 s8, s61, 7
	s_or_b32 s8, s8, s23
	s_ashr_i32 s8, s8, 6
	s_ashr_i32 s9, s8, 31
	s_lshl_b64 s[8:9], s[8:9], 15
	s_add_u32 s8, s36, s8
	s_addc_u32 s9, s63, s9
	s_mul_i32 s11, s79, 0x160000
	s_mul_hi_i32 s10, s79, 0x160000
	s_add_u32 s8, s8, s11
	s_addc_u32 s9, s9, s10
	v_mov_b32_e32 v209, v169
	v_mov_b32_e32 v140, 0xbfb8aa3b
	v_mov_b32_e32 v141, 0xbfb8aa3b
	v_mov_b32_e32 v142, 1.0
	v_mov_b32_e32 v143, 1.0
	v_pk_mul_f32 v[128:129], v[124:125], v[140:141]
	v_pk_mul_f32 v[130:131], v[126:127], v[140:141]
	v_pk_mul_f32 v[132:133], v[116:117], v[140:141]
	v_pk_mul_f32 v[134:135], v[118:119], v[140:141]
	v_exp_f32_e32 v128, v128
	v_exp_f32_e32 v129, v129
	v_exp_f32_e32 v130, v130
	v_exp_f32_e32 v131, v131
	v_exp_f32_e32 v132, v132
	v_exp_f32_e32 v133, v133
	v_exp_f32_e32 v134, v134
	v_exp_f32_e32 v135, v135
	v_pk_add_f32 v[128:129], v[128:129], v[142:143]
	v_pk_add_f32 v[130:131], v[130:131], v[142:143]
	v_pk_add_f32 v[132:133], v[132:133], v[142:143]
	v_pk_add_f32 v[134:135], v[134:135], v[142:143]
	v_rcp_f32_e32 v128, v128
	v_rcp_f32_e32 v129, v129
	v_rcp_f32_e32 v130, v130
	v_rcp_f32_e32 v131, v131
	v_rcp_f32_e32 v132, v132
	v_rcp_f32_e32 v133, v133
	v_rcp_f32_e32 v134, v134
	v_rcp_f32_e32 v135, v135
	v_pk_mul_f32 v[128:129], v[124:125], v[128:129]
	v_pk_mul_f32 v[130:131], v[126:127], v[130:131]
	v_pk_mul_f32 v[132:133], v[116:117], v[132:133]
	v_pk_mul_f32 v[134:135], v[118:119], v[134:135]
	v_pk_mul_f32 v[128:129], v[128:129], v[120:121]
	v_pk_mul_f32 v[130:131], v[130:131], v[122:123]
	v_pk_mul_f32 v[132:133], v[132:133], v[112:113]
	v_pk_mul_f32 v[134:135], v[134:135], v[114:115]
	v_cvt_pk_bf16_f32 v120, v128, v129
	v_cvt_pk_bf16_f32 v121, v130, v131
	v_cvt_pk_bf16_f32 v122, v132, v133
	v_cvt_pk_bf16_f32 v123, v134, v135
	v_lshl_add_u64 v[136:137], s[8:9], 0, v[182:183]
	v_lshl_add_u64 v[136:137], v[136:137], 0, v[208:209]
	global_store_dwordx4 v[136:137], v[120:123], off
	v_pk_mul_f32 v[128:129], v[108:109], v[140:141]
	v_pk_mul_f32 v[130:131], v[110:111], v[140:141]
	v_pk_mul_f32 v[132:133], v[100:101], v[140:141]
	v_pk_mul_f32 v[134:135], v[102:103], v[140:141]
	v_exp_f32_e32 v128, v128
	v_exp_f32_e32 v129, v129
	v_exp_f32_e32 v130, v130
	v_exp_f32_e32 v131, v131
	v_exp_f32_e32 v132, v132
	v_exp_f32_e32 v133, v133
	v_exp_f32_e32 v134, v134
	v_exp_f32_e32 v135, v135
	v_pk_add_f32 v[128:129], v[128:129], v[142:143]
	v_pk_add_f32 v[130:131], v[130:131], v[142:143]
	v_pk_add_f32 v[132:133], v[132:133], v[142:143]
	v_pk_add_f32 v[134:135], v[134:135], v[142:143]
	v_rcp_f32_e32 v128, v128
	v_rcp_f32_e32 v129, v129
	v_rcp_f32_e32 v130, v130
	v_rcp_f32_e32 v131, v131
	v_rcp_f32_e32 v132, v132
	v_rcp_f32_e32 v133, v133
	v_rcp_f32_e32 v134, v134
	v_rcp_f32_e32 v135, v135
	v_pk_mul_f32 v[128:129], v[108:109], v[128:129]
	v_pk_mul_f32 v[130:131], v[110:111], v[130:131]
	v_pk_mul_f32 v[132:133], v[100:101], v[132:133]
	v_pk_mul_f32 v[134:135], v[102:103], v[134:135]
	v_pk_mul_f32 v[128:129], v[128:129], v[104:105]
	v_pk_mul_f32 v[130:131], v[130:131], v[106:107]
	v_pk_mul_f32 v[132:133], v[132:133], v[96:97]
	v_pk_mul_f32 v[134:135], v[134:135], v[98:99]
	v_cvt_pk_bf16_f32 v104, v128, v129
	v_cvt_pk_bf16_f32 v105, v130, v131
	v_cvt_pk_bf16_f32 v106, v132, v133
	v_cvt_pk_bf16_f32 v107, v134, v135
	v_lshl_add_u64 v[136:137], s[8:9], 0, v[184:185]
	v_lshl_add_u64 v[136:137], v[136:137], 0, v[208:209]
	global_store_dwordx4 v[136:137], v[104:107], off
	v_pk_mul_f32 v[128:129], v[92:93], v[140:141]
	v_pk_mul_f32 v[130:131], v[94:95], v[140:141]
	v_pk_mul_f32 v[132:133], v[84:85], v[140:141]
	v_pk_mul_f32 v[134:135], v[86:87], v[140:141]
	v_exp_f32_e32 v128, v128
	v_exp_f32_e32 v129, v129
	v_exp_f32_e32 v130, v130
	v_exp_f32_e32 v131, v131
	v_exp_f32_e32 v132, v132
	v_exp_f32_e32 v133, v133
	v_exp_f32_e32 v134, v134
	v_exp_f32_e32 v135, v135
	v_pk_add_f32 v[128:129], v[128:129], v[142:143]
	v_pk_add_f32 v[130:131], v[130:131], v[142:143]
	v_pk_add_f32 v[132:133], v[132:133], v[142:143]
	v_pk_add_f32 v[134:135], v[134:135], v[142:143]
	v_rcp_f32_e32 v128, v128
	v_rcp_f32_e32 v129, v129
	v_rcp_f32_e32 v130, v130
	v_rcp_f32_e32 v131, v131
	v_rcp_f32_e32 v132, v132
	v_rcp_f32_e32 v133, v133
	v_rcp_f32_e32 v134, v134
	v_rcp_f32_e32 v135, v135
	v_pk_mul_f32 v[128:129], v[92:93], v[128:129]
	v_pk_mul_f32 v[130:131], v[94:95], v[130:131]
	v_pk_mul_f32 v[132:133], v[84:85], v[132:133]
	v_pk_mul_f32 v[134:135], v[86:87], v[134:135]
	v_pk_mul_f32 v[128:129], v[128:129], v[88:89]
	v_pk_mul_f32 v[130:131], v[130:131], v[90:91]
	v_pk_mul_f32 v[132:133], v[132:133], v[80:81]
	v_pk_mul_f32 v[134:135], v[134:135], v[82:83]
	v_cvt_pk_bf16_f32 v88, v128, v129
	v_cvt_pk_bf16_f32 v89, v130, v131
	v_cvt_pk_bf16_f32 v90, v132, v133
	v_cvt_pk_bf16_f32 v91, v134, v135
	v_lshl_add_u64 v[136:137], s[8:9], 0, v[186:187]
	v_lshl_add_u64 v[136:137], v[136:137], 0, v[208:209]
	global_store_dwordx4 v[136:137], v[88:91], off
	v_pk_mul_f32 v[128:129], v[76:77], v[140:141]
	v_pk_mul_f32 v[130:131], v[78:79], v[140:141]
	v_pk_mul_f32 v[132:133], v[68:69], v[140:141]
	v_pk_mul_f32 v[134:135], v[70:71], v[140:141]
	v_exp_f32_e32 v128, v128
	v_exp_f32_e32 v129, v129
	v_exp_f32_e32 v130, v130
	v_exp_f32_e32 v131, v131
	v_exp_f32_e32 v132, v132
	v_exp_f32_e32 v133, v133
	v_exp_f32_e32 v134, v134
	v_exp_f32_e32 v135, v135
	v_pk_add_f32 v[128:129], v[128:129], v[142:143]
	v_pk_add_f32 v[130:131], v[130:131], v[142:143]
	v_pk_add_f32 v[132:133], v[132:133], v[142:143]
	v_pk_add_f32 v[134:135], v[134:135], v[142:143]
	v_rcp_f32_e32 v128, v128
	v_rcp_f32_e32 v129, v129
	v_rcp_f32_e32 v130, v130
	v_rcp_f32_e32 v131, v131
	v_rcp_f32_e32 v132, v132
; __device__ __forceinline__ float silu_f(float x) { return x * __builtin_amdgcn_rcpf(1.f + __expf(-x)); }
; __device__ __forceinline__ unsigned cvt_pk_bf16(float lo, float hi) { unsigned r; asm("v_cvt_pk_bf16_f32 %0, %1, %2" : "=v"(r) : "v"(lo), "v"(hi)); return r; }
;     __device__ __forceinline__ void operator()(const f32x4 (&acc)[2][2][4][2], const Unit& u, int wr, int wc, int fr, int fq) const {
;     ...
;             for (int m = 0; m < 4; ++m) {
;                 const f32x4 g0 = acc[ai][0][m][0], u0 = acc[ai][1][m][0], g1 = acc[ai][0][m][1], u1 = acc[ai][1][m][1];
;                 u32x4 w;
;                 w.x = cvt_pk_bf16(silu_f(g0[0]) * u0[0], silu_f(g0[1]) * u0[1]); w.y = cvt_pk_bf16(silu_f(g0[2]) * u0[2], silu_f(g0[3]) * u0[3]);
;                 w.z = cvt_pk_bf16(silu_f(g1[0]) * u1[0], silu_f(g1[1]) * u1[1]); w.w = cvt_pk_bf16(silu_f(g1[2]) * u1[2], silu_f(g1[3]) * u1[3]);
;                 *(u32x4*)(O + (size_t)u.pm * BM * DFF + (size_t)(col >> 6) * (BM * 64) + (size_t)(wr * 64 + fr + ai * HALF + m * 16) * 64 + (col & 63)) = w;
;             }
;     }
	v_rcp_f32_e32 v133, v133
	v_rcp_f32_e32 v134, v134
	v_rcp_f32_e32 v135, v135
	v_pk_mul_f32 v[128:129], v[76:77], v[128:129]
	v_pk_mul_f32 v[130:131], v[78:79], v[130:131]
	v_pk_mul_f32 v[132:133], v[68:69], v[132:133]
	v_pk_mul_f32 v[134:135], v[70:71], v[134:135]
	v_pk_mul_f32 v[128:129], v[128:129], v[72:73]
	v_pk_mul_f32 v[130:131], v[130:131], v[74:75]
	v_pk_mul_f32 v[132:133], v[132:133], v[64:65]
	v_pk_mul_f32 v[134:135], v[134:135], v[66:67]
	v_cvt_pk_bf16_f32 v72, v128, v129
	v_cvt_pk_bf16_f32 v73, v130, v131
	v_cvt_pk_bf16_f32 v74, v132, v133
	v_cvt_pk_bf16_f32 v75, v134, v135
	v_lshl_add_u64 v[136:137], s[8:9], 0, v[188:189]
	v_lshl_add_u64 v[136:137], v[136:137], 0, v[208:209]
	global_store_dwordx4 v[136:137], v[72:75], off
	v_pk_mul_f32 v[128:129], v[60:61], v[140:141]
	v_pk_mul_f32 v[130:131], v[62:63], v[140:141]
	v_pk_mul_f32 v[132:133], v[52:53], v[140:141]
	v_pk_mul_f32 v[134:135], v[54:55], v[140:141]
	v_exp_f32_e32 v128, v128
	v_exp_f32_e32 v129, v129
	v_exp_f32_e32 v130, v130
	v_exp_f32_e32 v131, v131
	v_exp_f32_e32 v132, v132
	v_exp_f32_e32 v133, v133
	v_exp_f32_e32 v134, v134
	v_exp_f32_e32 v135, v135
	v_pk_add_f32 v[128:129], v[128:129], v[142:143]
	v_pk_add_f32 v[130:131], v[130:131], v[142:143]
	v_pk_add_f32 v[132:133], v[132:133], v[142:143]
	v_pk_add_f32 v[134:135], v[134:135], v[142:143]
	v_rcp_f32_e32 v128, v128
	v_rcp_f32_e32 v129, v129
	v_rcp_f32_e32 v130, v130
	v_rcp_f32_e32 v131, v131
	v_rcp_f32_e32 v132, v132
	v_rcp_f32_e32 v133, v133
	v_rcp_f32_e32 v134, v134
	v_rcp_f32_e32 v135, v135
	v_pk_mul_f32 v[128:129], v[60:61], v[128:129]
	v_pk_mul_f32 v[130:131], v[62:63], v[130:131]
	v_pk_mul_f32 v[132:133], v[52:53], v[132:133]
	v_pk_mul_f32 v[134:135], v[54:55], v[134:135]
	v_pk_mul_f32 v[128:129], v[128:129], v[56:57]
	v_pk_mul_f32 v[130:131], v[130:131], v[58:59]
	v_pk_mul_f32 v[132:133], v[132:133], v[48:49]
	v_pk_mul_f32 v[134:135], v[134:135], v[50:51]
	v_cvt_pk_bf16_f32 v56, v128, v129
	v_cvt_pk_bf16_f32 v57, v130, v131
	v_cvt_pk_bf16_f32 v58, v132, v133
	v_cvt_pk_bf16_f32 v59, v134, v135
	v_lshl_add_u64 v[136:137], s[8:9], 0, v[190:191]
	v_lshl_add_u64 v[136:137], v[136:137], 0, v[208:209]
	global_store_dwordx4 v[136:137], v[56:59], off
	v_pk_mul_f32 v[128:129], v[44:45], v[140:141]
	v_pk_mul_f32 v[130:131], v[46:47], v[140:141]
	v_pk_mul_f32 v[132:133], v[36:37], v[140:141]
	v_pk_mul_f32 v[134:135], v[38:39], v[140:141]
	v_exp_f32_e32 v128, v128
	v_exp_f32_e32 v129, v129
	v_exp_f32_e32 v130, v130
	v_exp_f32_e32 v131, v131
	v_exp_f32_e32 v132, v132
	v_exp_f32_e32 v133, v133
	v_exp_f32_e32 v134, v134
	v_exp_f32_e32 v135, v135
	v_pk_add_f32 v[128:129], v[128:129], v[142:143]
	v_pk_add_f32 v[130:131], v[130:131], v[142:143]
	v_pk_add_f32 v[132:133], v[132:133], v[142:143]
	v_pk_add_f32 v[134:135], v[134:135], v[142:143]
	v_rcp_f32_e32 v128, v128
	v_rcp_f32_e32 v129, v129
	v_rcp_f32_e32 v130, v130
	v_rcp_f32_e32 v131, v131
	v_rcp_f32_e32 v132, v132
	v_rcp_f32_e32 v133, v133
	v_rcp_f32_e32 v134, v134
	v_rcp_f32_e32 v135, v135
	v_pk_mul_f32 v[128:129], v[44:45], v[128:129]
	v_pk_mul_f32 v[130:131], v[46:47], v[130:131]
	v_pk_mul_f32 v[132:133], v[36:37], v[132:133]
	v_pk_mul_f32 v[134:135], v[38:39], v[134:135]
	v_pk_mul_f32 v[128:129], v[128:129], v[40:41]
	v_pk_mul_f32 v[130:131], v[130:131], v[42:43]
	v_pk_mul_f32 v[132:133], v[132:133], v[32:33]
	v_pk_mul_f32 v[134:135], v[134:135], v[34:35]
	v_cvt_pk_bf16_f32 v40, v128, v129
	v_cvt_pk_bf16_f32 v41, v130, v131
	v_cvt_pk_bf16_f32 v42, v132, v133
	v_cvt_pk_bf16_f32 v43, v134, v135
	v_lshl_add_u64 v[136:137], s[8:9], 0, v[192:193]
	v_lshl_add_u64 v[136:137], v[136:137], 0, v[208:209]
	global_store_dwordx4 v[136:137], v[40:43], off
	v_pk_mul_f32 v[128:129], v[28:29], v[140:141]
	v_pk_mul_f32 v[130:131], v[30:31], v[140:141]
	v_pk_mul_f32 v[132:133], v[20:21], v[140:141]
	v_pk_mul_f32 v[134:135], v[22:23], v[140:141]
	v_exp_f32_e32 v128, v128
	v_exp_f32_e32 v129, v129
	v_exp_f32_e32 v130, v130
	v_exp_f32_e32 v131, v131
	v_exp_f32_e32 v132, v132
	v_exp_f32_e32 v133, v133
	v_exp_f32_e32 v134, v134
	v_exp_f32_e32 v135, v135
	v_pk_add_f32 v[128:129], v[128:129], v[142:143]
	v_pk_add_f32 v[130:131], v[130:131], v[142:143]
	v_pk_add_f32 v[132:133], v[132:133], v[142:143]
	v_pk_add_f32 v[134:135], v[134:135], v[142:143]
	v_rcp_f32_e32 v128, v128
	v_rcp_f32_e32 v129, v129
	v_rcp_f32_e32 v130, v130
	v_rcp_f32_e32 v131, v131
	v_rcp_f32_e32 v132, v132
	v_rcp_f32_e32 v133, v133
	v_rcp_f32_e32 v134, v134
	v_rcp_f32_e32 v135, v135
	v_pk_mul_f32 v[128:129], v[28:29], v[128:129]
	v_pk_mul_f32 v[130:131], v[30:31], v[130:131]
	v_pk_mul_f32 v[132:133], v[20:21], v[132:133]
	v_pk_mul_f32 v[134:135], v[22:23], v[134:135]
	v_pk_mul_f32 v[128:129], v[128:129], v[24:25]
	v_pk_mul_f32 v[130:131], v[130:131], v[26:27]
	v_pk_mul_f32 v[132:133], v[132:133], v[16:17]
	v_pk_mul_f32 v[134:135], v[134:135], v[18:19]
	v_cvt_pk_bf16_f32 v24, v128, v129
	v_cvt_pk_bf16_f32 v25, v130, v131
	v_cvt_pk_bf16_f32 v26, v132, v133
	v_cvt_pk_bf16_f32 v27, v134, v135
	v_lshl_add_u64 v[136:137], s[8:9], 0, v[194:195]
	v_lshl_add_u64 v[136:137], v[136:137], 0, v[208:209]
	global_store_dwordx4 v[136:137], v[24:27], off
	v_pk_mul_f32 v[128:129], v[12:13], v[140:141]
	v_pk_mul_f32 v[130:131], v[14:15], v[140:141]
	v_pk_mul_f32 v[132:133], v[4:5], v[140:141]
	v_pk_mul_f32 v[134:135], v[6:7], v[140:141]
	v_exp_f32_e32 v128, v128
	v_exp_f32_e32 v129, v129
	v_exp_f32_e32 v130, v130
	v_exp_f32_e32 v131, v131
	v_exp_f32_e32 v132, v132
	v_exp_f32_e32 v133, v133
	v_exp_f32_e32 v134, v134
	v_exp_f32_e32 v135, v135
	v_pk_add_f32 v[128:129], v[128:129], v[142:143]
	v_pk_add_f32 v[130:131], v[130:131], v[142:143]
	v_pk_add_f32 v[132:133], v[132:133], v[142:143]
	v_pk_add_f32 v[134:135], v[134:135], v[142:143]
	v_rcp_f32_e32 v128, v128
	v_rcp_f32_e32 v129, v129
	v_rcp_f32_e32 v130, v130
	v_rcp_f32_e32 v131, v131
	v_rcp_f32_e32 v132, v132
	v_rcp_f32_e32 v133, v133
	v_rcp_f32_e32 v134, v134
	v_rcp_f32_e32 v135, v135
	v_pk_mul_f32 v[128:129], v[12:13], v[128:129]
	v_pk_mul_f32 v[130:131], v[14:15], v[130:131]
	v_pk_mul_f32 v[132:133], v[4:5], v[132:133]
	v_pk_mul_f32 v[134:135], v[6:7], v[134:135]
	v_pk_mul_f32 v[128:129], v[128:129], v[8:9]
	v_pk_mul_f32 v[130:131], v[130:131], v[10:11]
	v_pk_mul_f32 v[132:133], v[132:133], v[0:1]
	v_pk_mul_f32 v[134:135], v[134:135], v[2:3]
	v_cvt_pk_bf16_f32 v8, v128, v129
	v_cvt_pk_bf16_f32 v9, v130, v131
	v_cvt_pk_bf16_f32 v10, v132, v133
	v_cvt_pk_bf16_f32 v11, v134, v135
	v_lshl_add_u64 v[136:137], s[8:9], 0, v[196:197]
	v_lshl_add_u64 v[136:137], v[136:137], 0, v[208:209]
	global_store_dwordx4 v[136:137], v[8:11], off
	s_and_b64 vcc, exec, s[6:7]
	s_mov_b64 s[6:7], -1
	s_cbranch_vccnz .LBB0_145
	s_branch .LBB0_343
